# grid sync after the prologue phase now uses the XCD-hierarchical barrier instead of cooperative-groups grid sync
# baseline (speedup 1.0000x reference)
; #define LAS __attribute__((address_space(3)))
; __device__ __forceinline__ unsigned xb_ld(unsigned* p)              { return __hip_atomic_load(p, __ATOMIC_RELAXED, __HIP_MEMORY_SCOPE_AGENT); }
; __device__ __forceinline__ unsigned xb_xcc_id() { return (unsigned)__builtin_amdgcn_s_getreg((3 << 11) | 20) & 0xFu; }
; __device__ __forceinline__ void xcd_barrier(const XcdBarrier& b) {
;     asm volatile("s_waitcnt vmcnt(0)" ::: "memory");
;     __syncthreads();
;     if (threadIdx.x == 0) {
;         unsigned* bar = b.bar;
;         __builtin_amdgcn_s_waitcnt(0);
;         unsigned nloc = b.st[0], nx = b.st[1];
;         if (nloc == 0u) { xcd_barrier_complete(bar, b.x, nloc, nx); b.st[0] = nloc; b.st[1] = nx; }
; __global__ void __launch_bounds__(NTHREADS) mega_kernel(Params p_) {
;     ...
;         if (coop && ph + 1 < ph_hi) {
;             if (ph == 0) {
;                 cg::this_grid().sync();
;                 volatile LAS unsigned* st_ = (volatile LAS unsigned*)(F.lds + 131072 + 64);
;                 if (threadIdx.x == 0) {
;                     unsigned* bar_ = (unsigned*)F.ws; bool ok_ = (gridDim.x % 8u) == 0u;
;                     for (unsigned j = 0; j < 16; ++j) { const unsigned c_ = xb_ld(&bar_[XB_XCNT(j)]); ok_ = ok_ && (c_ == (j < 8u ? gridDim.x / 8u : 0u)); }
;                     const unsigned x_ = xb_xcc_id();
;                     st_[3] = (ok_ && x_ < 8u && st_[2] < gridDim.x / 8u) ? (st_[2] * 8u + x_) : blockIdx.x;
;                 }
;                 __syncthreads();
;             }
;             else { XcdBarrier xb_; xb_.bar = (unsigned*)F.ws; xb_.x = xb_xcc_id(); xb_.st = (volatile LAS unsigned*)(F.lds + 131072 + 64); xcd_barrier(xb_); if (SYNC2) xcd_barrier(xb_); }
.LBB0_622:
	v_readlane_b32 s12, v254, 16
	v_readlane_b32 s13, v254, 17
	s_add_i32 s26, s12, 1
	s_cmp_ge_i32 s26, s13
	s_cselect_b64 s[0:1], -1, 0
	s_cmp_lt_i32 s26, s13
	v_readlane_b32 s6, v254, 3
	s_cselect_b64 s[4:5], -1, 0
	v_readlane_b32 s7, v254, 4
	s_and_b64 s[4:5], s[6:7], s[4:5]
	s_andn2_b64 vcc, exec, s[4:5]
	v_readlane_b32 s14, v254, 18
	v_readlane_b32 s15, v254, 19
	s_cbranch_vccnz .LBB0_17
	s_getreg_b32 s6, hwreg(HW_REG_XCC_ID, 0, 4)
	s_waitcnt vmcnt(0)
	s_waitcnt vmcnt(0) lgkmcnt(0)
	s_barrier
	s_mov_b64 s[4:5], exec
	v_readlane_b32 s8, v254, 8
	v_readlane_b32 s9, v254, 9
	s_and_b64 s[8:9], s[4:5], s[8:9]
	s_mov_b64 exec, s[8:9]
	s_cbranch_execz .LBB0_1139
	v_readlane_b32 s7, v254, 12
	s_waitcnt vmcnt(0) expcnt(0) lgkmcnt(0)
	s_and_b32 s20, s6, 15
	v_mov_b32_e32 v0, s7
	ds_read_b32 v2, v0
	v_readlane_b32 s7, v254, 13
	s_waitcnt lgkmcnt(0)
	v_cmp_ne_u32_e32 vcc, 0, v2
	v_mov_b32_e32 v0, s7
	ds_read_b32 v0, v0
	s_cbranch_vccnz .LBB0_774
	v_readlane_b32 s6, v254, 6
	v_readlane_b32 s7, v254, 7
	s_load_dwordx2 s[10:11], s[6:7], 0x4
	s_add_u32 s6, s90, 0x1000
	s_addc_u32 s7, s91, 0
	s_add_u32 s8, s90, 0x1100
	s_addc_u32 s9, s91, 0
	s_waitcnt lgkmcnt(0)
	s_mul_i32 s21, s10, s82
	s_add_u32 s10, s90, 0x1200
	s_mul_i32 s21, s21, s11
	s_addc_u32 s11, s91, 0
	s_add_u32 s12, s90, 0x1300
	s_addc_u32 s13, s91, 0
	s_mov_b32 s22, 1
	s_branch .LBB0_628

; #define LAS __attribute__((address_space(3)))
; __device__ __forceinline__ unsigned xb_ld(unsigned* p)              { return __hip_atomic_load(p, __ATOMIC_RELAXED, __HIP_MEMORY_SCOPE_AGENT); }
; __device__ __forceinline__ unsigned xb_xcc_id() { return (unsigned)__builtin_amdgcn_s_getreg((3 << 11) | 20) & 0xFu; }
; __device__ __forceinline__ void xcd_barrier(const XcdBarrier& b) {
;     ...
;     }
;     __syncthreads();
; }
; __global__ void __launch_bounds__(NTHREADS) mega_kernel(Params p_) {
;     ...
;             if (ph == 0) {
;                 cg::this_grid().sync();
;                 volatile LAS unsigned* st_ = (volatile LAS unsigned*)(F.lds + 131072 + 64);
;                 if (threadIdx.x == 0) {
;                     unsigned* bar_ = (unsigned*)F.ws; bool ok_ = (gridDim.x % 8u) == 0u;
;                     for (unsigned j = 0; j < 16; ++j) { const unsigned c_ = xb_ld(&bar_[XB_XCNT(j)]); ok_ = ok_ && (c_ == (j < 8u ? gridDim.x / 8u : 0u)); }
;                     const unsigned x_ = xb_xcc_id();
;                     st_[3] = (ok_ && x_ < 8u && st_[2] < gridDim.x / 8u) ? (st_[2] * 8u + x_) : blockIdx.x;
;                 }
;                 __syncthreads();
.LBB0_1139:
	s_or_b64 exec, exec, s[4:5]
	s_waitcnt lgkmcnt(0)
	s_barrier
	v_readlane_b32 s6, v254, 16
	s_nop 0
	s_cmp_eq_u32 s6, 0
	s_cbranch_scc1 .Lph0_remap
	s_getpc_b64 s[98:99]

; #define LAS __attribute__((address_space(3)))
; __device__ __forceinline__ unsigned xb_ld(unsigned* p)              { return __hip_atomic_load(p, __ATOMIC_RELAXED, __HIP_MEMORY_SCOPE_AGENT); }
; __device__ __forceinline__ unsigned xb_xcc_id() { return (unsigned)__builtin_amdgcn_s_getreg((3 << 11) | 20) & 0xFu; }
; __global__ void __launch_bounds__(NTHREADS) mega_kernel(Params p_) {
;     ...
;                 volatile LAS unsigned* st_ = (volatile LAS unsigned*)(F.lds + 131072 + 64);
;                 if (threadIdx.x == 0) {
;                     unsigned* bar_ = (unsigned*)F.ws; bool ok_ = (gridDim.x % 8u) == 0u;
;                     for (unsigned j = 0; j < 16; ++j) { const unsigned c_ = xb_ld(&bar_[XB_XCNT(j)]); ok_ = ok_ && (c_ == (j < 8u ? gridDim.x / 8u : 0u)); }
;                     const unsigned x_ = xb_xcc_id();
;                     st_[3] = (ok_ && x_ < 8u && st_[2] < gridDim.x / 8u) ? (st_[2] * 8u + x_) : blockIdx.x;
;                 }
;                 __syncthreads();
.Lph0_remap:
	s_mov_b64 s[4:5], exec
	v_readlane_b32 s6, v254, 8
	v_readlane_b32 s7, v254, 9
	s_and_b64 s[6:7], s[4:5], s[6:7]
	s_mov_b64 exec, s[6:7]
	s_cbranch_execnz .LBB0_1151
	s_getpc_b64 s[98:99]
